# hg<true>: LF converts + next-chunk decay totals computed behind the last step-3 MFMA (replaces its s_nop), only the TOT store stays after the OS writes
# speedup vs baseline: 1.0039x; 1.0014x over previous
; #define LAS __attribute__((address_space(3)))
; template <bool FULL, bool STORE = true>
; __device__ __forceinline__ void hg_item(const Prm& P, LAS unsigned char* lds, int item, int wave) {
;     ...
;         for (int i = 0; i < 8; ++i) { f0[i] = __expf(c0[i]); f1[i] = __expf(c1[i]); ka[i] = 1.0f - f0[i]; kc[i] = 1.0f - f1[i]; t0 += c0[i]; t1 += c1[i]; }
;         *(LAS f32x2*)(lds + HL_TOT + (tg * 128 + k2) * 4) = (f32x2){t0, t1};
;     ...
;                 for (int ks = 0; ks < 8; ++ks) { const bf16x8 a = *(const LAS bf16x8*)(lds + HL_QD + (tb * 32 + l31) * 272 + ks * 32 + lh * 16), bb = *(const LAS bf16x8*)(lds + HL_ST + (vb * 32 + l31) * 272 + ks * 32 + lh * 16);
;                     o = __builtin_amdgcn_mfma_f32_32x32x16_bf16(a, bb, o, 0, 0, 0); }
; #pragma unroll
;                 for (int r = 0; r < 16; ++r) { const int t = tb * 32 + (r & 3) + 8 * (r >> 2) + 4 * lh; *(LAS float*)(lds + HL_OS + t * 528 + (vb * 32 + l31) * 4) = o[r]; }
.LBB0_839:
	s_mov_b32 s33, 0x800000
	s_add_u32 s86, s86, 0x20000
	s_addc_u32 s87, s87, 0
	v_lshlrev_b32_e32 v104, 16, v52
	v_and_b32_e32 v105, 0xffff0000, v52
	v_lshlrev_b32_e32 v52, 16, v53
	v_and_b32_e32 v53, 0xffff0000, v53
	s_add_u32 s84, s84, 0x10000
	s_addc_u32 s85, s85, 0
	s_cmp_lg_u32 s86, 0x200000
	s_waitcnt lgkmcnt(6)
	v_mfma_f32_32x32x16_bf16 v[32:47], v[172:175], v[176:179], v[32:47]
	ds_read_b128 v[172:175], v151 offset:34944
	ds_read_b128 v[176:179], v152 offset:128
	v_pk_mul_f32 v[0:1], v[0:1], v[78:79]
	v_pk_mul_f32 v[2:3], v[2:3], v[80:81]
	s_waitcnt lgkmcnt(6)
	v_mfma_f32_32x32x16_bf16 v[32:47], v[180:183], v[184:187], v[32:47]
	ds_read_b128 v[180:183], v151 offset:34976
	ds_read_b128 v[184:187], v152 offset:160
	v_pk_mul_f32 v[16:17], v[16:17], v[78:79]
	v_pk_mul_f32 v[18:19], v[18:19], v[80:81]
	s_waitcnt lgkmcnt(6)
	v_mfma_f32_32x32x16_bf16 v[32:47], v[188:191], v[192:195], v[32:47]
	ds_read_b128 v[188:191], v151 offset:35008
	ds_read_b128 v[192:195], v152 offset:192
	v_pk_mul_f32 v[4:5], v[4:5], v[82:83]
	v_pk_mul_f32 v[6:7], v[6:7], v[84:85]
	s_waitcnt lgkmcnt(6)
	v_mfma_f32_32x32x16_bf16 v[32:47], v[196:199], v[200:203], v[32:47]
	ds_read_b128 v[196:199], v151 offset:35040
	ds_read_b128 v[200:203], v152 offset:224
	ds_read_b128 v[204:207], v155 offset:4608
	ds_read_b128 v[208:211], v155 offset:4640
	ds_read_b128 v[212:215], v155 offset:4672
	ds_read_b128 v[216:219], v155 offset:4704
	v_pk_mul_f32 v[20:21], v[20:21], v[82:83]
	v_pk_mul_f32 v[22:23], v[22:23], v[84:85]
	s_waitcnt lgkmcnt(10)
	v_mfma_f32_32x32x16_bf16 v[32:47], v[172:175], v[176:179], v[32:47]
	v_pk_mul_f32 v[8:9], v[8:9], v[86:87]
	v_pk_mul_f32 v[10:11], v[10:11], v[88:89]
	ds_read_b128 v[172:175], v154 offset:52224
	ds_read_b128 v[176:179], v154 offset:52256
	s_waitcnt lgkmcnt(10)
	v_mfma_f32_32x32x16_bf16 v[32:47], v[180:183], v[184:187], v[32:47]
	v_pk_mul_f32 v[24:25], v[24:25], v[86:87]
	v_pk_mul_f32 v[26:27], v[26:27], v[88:89]
	ds_read_b128 v[180:183], v154 offset:52288
	ds_read_b128 v[184:187], v154 offset:52320
	s_waitcnt lgkmcnt(10)
	v_mfma_f32_32x32x16_bf16 v[32:47], v[188:191], v[192:195], v[32:47]
	v_pk_mul_f32 v[12:13], v[12:13], v[90:91]
	v_pk_mul_f32 v[14:15], v[14:15], v[92:93]
	ds_read_b128 v[188:191], v155
	ds_read_b128 v[192:195], v155 offset:32
	s_waitcnt lgkmcnt(10)
	v_mfma_f32_32x32x16_bf16 v[32:47], v[196:199], v[200:203], v[32:47]
	v_pk_mul_f32 v[28:29], v[28:29], v[90:91]
	v_pk_mul_f32 v[30:31], v[30:31], v[92:93]
	ds_read_b128 v[196:199], v155 offset:64
	ds_read_b128 v[200:203], v155 offset:96
	s_waitcnt vmcnt(18)
	v_cvt_f32_f16_e32 v78, v240
	v_cvt_f32_f16_sdwa v79, v240 dst_sel:DWORD dst_unused:UNUSED_PAD src0_sel:WORD_1
	v_cvt_f32_f16_e32 v80, v241
	v_cvt_f32_f16_sdwa v81, v241 dst_sel:DWORD dst_unused:UNUSED_PAD src0_sel:WORD_1
	v_cvt_f32_f16_e32 v82, v242
	v_cvt_f32_f16_sdwa v83, v242 dst_sel:DWORD dst_unused:UNUSED_PAD src0_sel:WORD_1
	v_cvt_f32_f16_e32 v84, v243
	v_cvt_f32_f16_sdwa v85, v243 dst_sel:DWORD dst_unused:UNUSED_PAD src0_sel:WORD_1
	v_cvt_f32_f16_e32 v86, v244
	v_cvt_f32_f16_sdwa v87, v244 dst_sel:DWORD dst_unused:UNUSED_PAD src0_sel:WORD_1
	v_cvt_f32_f16_e32 v88, v245
	v_cvt_f32_f16_sdwa v89, v245 dst_sel:DWORD dst_unused:UNUSED_PAD src0_sel:WORD_1
	v_cvt_f32_f16_e32 v90, v246
	v_cvt_f32_f16_sdwa v91, v246 dst_sel:DWORD dst_unused:UNUSED_PAD src0_sel:WORD_1
	v_cvt_f32_f16_e32 v92, v247
	v_cvt_f32_f16_sdwa v93, v247 dst_sel:DWORD dst_unused:UNUSED_PAD src0_sel:WORD_1
	s_nop 0
	v_pk_add_f32 v[98:99], v[78:79], 0 op_sel_hi:[1,0]
	v_pk_add_f32 v[98:99], v[98:99], v[80:81]
	v_pk_add_f32 v[98:99], v[98:99], v[82:83]
	v_pk_add_f32 v[98:99], v[98:99], v[84:85]
	v_pk_add_f32 v[98:99], v[98:99], v[86:87]
	v_pk_add_f32 v[98:99], v[98:99], v[88:89]
	v_pk_add_f32 v[98:99], v[98:99], v[90:91]
	v_pk_add_f32 v[98:99], v[98:99], v[92:93]
	v_add_u32_e32 v100, s60, v126
	ds_write2_b32 v153, v32, v33 offset1:132
	v_add_u32_e32 v32, 0x400, v153
	ds_write2_b32 v32, v34, v35 offset0:8 offset1:140
	v_add_u32_e32 v32, 0x1000, v153
	ds_write2_b32 v32, v36, v37 offset0:32 offset1:164
	v_add_u32_e32 v32, 0x1400, v153
	ds_write2_b32 v32, v38, v39 offset0:40 offset1:172
	v_add_u32_e32 v32, 0x2000, v153
	ds_write2_b32 v32, v40, v41 offset0:64 offset1:196
	v_add_u32_e32 v32, 0x2400, v153
	ds_write2_b32 v32, v42, v43 offset0:72 offset1:204
	v_add_u32_e32 v32, 0x3000, v153
	ds_write2_b32 v32, v44, v45 offset0:96 offset1:228
	v_add_u32_e32 v32, 0x3400, v153
	ds_write2_b32 v32, v46, v47 offset0:104 offset1:236
	ds_write_b64 v100, v[98:99]
	s_waitcnt lgkmcnt(0)
	s_barrier
; #define LAS __attribute__((address_space(3)))
; __device__ __forceinline__ unsigned pk2(float lo, float hi) { typedef float f2v __attribute__((ext_vector_type(2))); typedef __bf16 b2v __attribute__((ext_vector_type(2))); const f2v v = {lo, hi}; const b2v b = __builtin_convertvector(v, b2v); return __builtin_bit_cast(unsigned, b); }
; template <bool FULL, bool STORE = true>
; __device__ __forceinline__ void hg_item(const Prm& P, LAS unsigned char* lds, int item, int wave) {
;     ...
;         for (int ks = 0; ks < 4; ++ks) { const bf16x8 a = *(const LAS bf16x8*)(lds + HL_KDT + (kb * 32 + l31) * 144 + ks * 32 + lh * 16);
; #pragma unroll
;             for (int i = 0; i < 2; ++i) { const bf16x8 bb = *(const LAS bf16x8*)(lds + HL_IVT + ((vb0 + i) * 32 + l31) * 144 + ks * 32 + lh * 16); S[i] = __builtin_amdgcn_mfma_f32_32x32x16_bf16(a, bb, S[i], 0, 0, 0); } }
;         if (FULL) {
;             __syncthreads();
; #pragma unroll
;             for (int i = 0; i < 2; ++i)
; #pragma unroll
;                 for (int g4 = 0; g4 < 4; ++g4) { u32x2 w; w.x = pk2(S[i][4 * g4], S[i][4 * g4 + 1]); w.y = pk2(S[i][4 * g4 + 2], S[i][4 * g4 + 3]);
;                     *(LAS u32x2*)(lds + HL_ST + ((vb0 + i) * 32 + l31) * 272 + (kb * 32 + 8 * g4 + 4 * lh) * 2) = w; }
;             { const int t = tid >> 3, vs = (tid & 7) * 16; float o[16]; float ss = 0.f;
; #pragma unroll
;                 for (int q4 = 0; q4 < 4; ++q4) { const f32x4 x4 = *(const LAS f32x4*)(lds + HL_OS + t * 528 + (vs + 4 * q4) * 4);
; #pragma unroll
;                     for (int j = 0; j < 4; ++j) { o[4 * q4 + j] = x4[j]; ss += x4[j] * x4[j]; } }
;                 ss += __shfl_xor(ss, 1); ss += __shfl_xor(ss, 2); ss += __shfl_xor(ss, 4);
;                 const float r = rsqrtf(ss * (1.0f / 128.0f) + EPS);
;                 const size_t oo = (row0 + t) * 1024 + h * 128 + vs; const float* gn = P.in[I_HGNG] + h * 128 + vs;
;                 float g0[8], g1[8]; unpack8(gcur0, g0); unpack8(gcur1, g1);
;                 float w0[8], w1[8];
; #pragma unroll
;                 for (int j = 0; j < 8; ++j) { w0[j] = o[j] * r * gn[j] * g0[j]; w1[j] = o[8 + j] * r * gn[8 + j] * g1[j]; }
;                 if (STORE) { *(u32x4*)(AHG + oo) = pack8(w0); *(u32x4*)(AHG + oo + 8) = pack8(w1); }
;             }
	ds_read_b128 v[66:69], v157
	ds_read_b128 v[36:39], v157 offset:16
	ds_read_b128 v[44:47], v157 offset:32
	ds_read_b128 v[32:35], v157 offset:48
	s_waitcnt lgkmcnt(3)
	v_mul_f32_e32 v64, v67, v67
	v_mfma_f32_32x32x16_bf16 v[0:15], v[172:175], v[188:191], v[0:15]
	v_fmac_f32_e32 v64, v66, v66
	v_fmac_f32_e32 v64, v68, v68
	v_fmac_f32_e32 v64, v69, v69
	s_waitcnt lgkmcnt(2)
	v_fmac_f32_e32 v64, v36, v36
	v_fmac_f32_e32 v64, v37, v37
	v_fmac_f32_e32 v64, v38, v38
	v_fmac_f32_e32 v64, v39, v39
	v_mfma_f32_32x32x16_bf16 v[16:31], v[172:175], v[204:207], v[16:31]
	s_waitcnt lgkmcnt(1)
	v_pk_mul_f32 v[42:43], v[44:45], v[44:45]
	v_pk_mul_f32 v[40:41], v[46:47], v[46:47]
	v_add_f32_e32 v42, v42, v64
	v_add_f32_e32 v42, v43, v42
	v_add_f32_e32 v40, v40, v42
	v_add_f32_e32 v64, v41, v40
	s_waitcnt lgkmcnt(0)
	s_barrier
	v_pk_mul_f32 v[42:43], v[32:33], v[32:33]
	v_mfma_f32_32x32x16_bf16 v[0:15], v[176:179], v[192:195], v[0:15]
	v_pk_mul_f32 v[40:41], v[34:35], v[34:35]
	v_add_f32_e32 v42, v42, v64
	v_add_f32_e32 v42, v43, v42
	v_add_f32_e32 v40, v40, v42
	v_add_f32_e32 v40, v41, v40
	s_nop 1
	v_add_f32_dpp v40, v40, v40 quad_perm:[1,0,3,2] row_mask:0xf bank_mask:0xf
	s_nop 1
	v_add_f32_dpp v40, v40, v40 quad_perm:[2,3,0,1] row_mask:0xf bank_mask:0xf
	v_mfma_f32_32x32x16_bf16 v[16:31], v[176:179], v[208:211], v[16:31]
	s_nop 1
	v_add_f32_dpp v40, v40, v40 row_half_mirror row_mask:0xf bank_mask:0xf
	v_fmamk_f32 v40, v40, 0x3c000000, v109
	v_cmp_gt_f32_e32 vcc, s33, v40
	v_mul_f32_e32 v41, 0x4b800000, v40
	s_mov_b32 s33, 0x7400000
	v_cndmask_b32_e32 v40, v40, v41, vcc
	v_rsq_f32_e32 v40, v40
	s_nop 0
	v_mul_f32_e32 v41, 0x45800000, v40
	v_mfma_f32_32x32x16_bf16 v[0:15], v[180:183], v[196:199], v[0:15]
	v_cndmask_b32_e32 v74, v40, v41, vcc
	v_pk_mul_f32 v[106:107], v[66:67], v[74:75] op_sel_hi:[1,0]
	v_pk_mul_f32 v[46:47], v[46:47], v[74:75] op_sel_hi:[1,0]
	v_pk_mul_f32 v[36:37], v[36:37], v[74:75] op_sel_hi:[1,0]
	v_pk_mul_f32 v[32:33], v[32:33], v[74:75] op_sel_hi:[1,0]
	v_pk_mul_f32 v[44:45], v[44:45], v[74:75] op_sel_hi:[1,0]
	v_pk_mul_f32 v[38:39], v[38:39], v[74:75] op_sel_hi:[1,0]
	v_mfma_f32_32x32x16_bf16 v[16:31], v[180:183], v[212:215], v[16:31]
	v_pk_mul_f32 v[34:35], v[34:35], v[74:75] op_sel_hi:[1,0]
	v_pk_mul_f32 v[32:33], v[224:225], v[32:33]
	v_pk_mul_f32 v[46:47], v[230:231], v[46:47]
	v_pk_mul_f32 v[36:37], v[232:233], v[36:37]
	v_pk_mul_f32 v[106:107], v[236:237], v[106:107]
	v_pk_mul_f32 v[44:45], v[228:229], v[44:45]
	v_pk_mul_f32 v[104:105], v[106:107], v[104:105]
	v_mfma_f32_32x32x16_bf16 v[0:15], v[184:187], v[200:203], v[0:15]
	v_lshlrev_b32_e32 v106, 16, v48
	v_and_b32_e32 v107, 0xffff0000, v48
	v_lshlrev_b32_e32 v48, 16, v49
	v_and_b32_e32 v49, 0xffff0000, v49
	v_pk_mul_f32 v[46:47], v[46:47], v[48:49]
	v_lshlrev_b32_e32 v48, 16, v54
	v_and_b32_e32 v49, 0xffff0000, v54
	v_mfma_f32_32x32x16_bf16 v[16:31], v[184:187], v[216:219], v[16:31]
	v_pk_mul_f32 v[36:37], v[36:37], v[48:49]
	v_lshlrev_b32_e32 v48, 16, v50
	v_and_b32_e32 v49, 0xffff0000, v50
	v_pk_mul_f32 v[64:65], v[68:69], v[74:75] op_sel_hi:[1,0]
	v_pk_mul_f32 v[40:41], v[32:33], v[48:49]
	v_lshlrev_b32_e32 v32, 16, v55
	v_and_b32_e32 v33, 0xffff0000, v55
	v_pk_mul_f32 v[38:39], v[234:235], v[38:39]
	v_pk_mul_f32 v[64:65], v[238:239], v[64:65]
	v_pk_mul_f32 v[38:39], v[38:39], v[32:33]
	v_lshlrev_b32_e32 v32, 16, v51
	v_and_b32_e32 v33, 0xffff0000, v51
	v_pk_mul_f32 v[34:35], v[226:227], v[34:35]
	v_pk_mul_f32 v[52:53], v[64:65], v[52:53]
	v_pk_mul_f32 v[42:43], v[34:35], v[32:33]
	v_cvt_pk_bf16_f32 v34, v36, v37
	v_add_co_u32_e32 v36, vcc, s33, v102
	v_pk_mul_f32 v[44:45], v[44:45], v[106:107]
	v_cvt_pk_bf16_f32 v32, v104, v105
	v_cvt_pk_bf16_f32 v33, v52, v53
	v_cvt_pk_bf16_f32 v35, v38, v39
	v_addc_co_u32_e32 v37, vcc, 0, v103, vcc
	s_waitcnt vmcnt(0)
	v_mov_b64_e32 v[52:53], v[56:57]
	v_mov_b64_e32 v[48:49], v[60:61]
	global_store_dwordx4 v[36:37], v[32:35], off
	v_mov_b64_e32 v[54:55], v[58:59]
	v_mov_b64_e32 v[50:51], v[62:63]
	v_cvt_pk_bf16_f32 v32, v44, v45
	v_cvt_pk_bf16_f32 v33, v46, v47
	v_cvt_pk_bf16_f32 v34, v40, v41
	v_cvt_pk_bf16_f32 v35, v42, v43
	global_store_dwordx4 v[36:37], v[32:35], off offset:16
	s_nop 8
	v_cvt_pk_bf16_f32 v32, v0, v1
	v_cvt_pk_bf16_f32 v33, v2, v3
	v_cvt_pk_bf16_f32 v34, v4, v5
	v_cvt_pk_bf16_f32 v35, v6, v7
	ds_write2_b64 v156, v[32:33], v[34:35] offset1:2
	v_cvt_pk_bf16_f32 v32, v8, v9
	v_cvt_pk_bf16_f32 v33, v10, v11
	v_cvt_pk_bf16_f32 v34, v12, v13
	v_cvt_pk_bf16_f32 v35, v14, v15
	ds_write2_b64 v156, v[32:33], v[34:35] offset0:4 offset1:6
	v_cvt_pk_bf16_f32 v32, v16, v17
	v_cvt_pk_bf16_f32 v33, v18, v19
	v_cvt_pk_bf16_f32 v34, v20, v21
	v_cvt_pk_bf16_f32 v35, v22, v23
	v_add_u32_e32 v36, 0x2000, v156
	ds_write2_b64 v36, v[32:33], v[34:35] offset0:64 offset1:66
	v_cvt_pk_bf16_f32 v32, v24, v25
	v_cvt_pk_bf16_f32 v33, v26, v27
	v_cvt_pk_bf16_f32 v34, v28, v29
	v_cvt_pk_bf16_f32 v35, v30, v31
	ds_write2_b64 v36, v[32:33], v[34:35] offset0:68 offset1:70
	s_cbranch_scc0 .LBB0_821
